# P0 h1=rmsnorm(x): the x rows are fetched with the nt cache policy
# speedup vs baseline: 1.0147x; 1.0061x over previous
.LBB0_52:
	s_or_b64 exec, exec, s[24:25]
	v_add_u32_e32 v4, 0xffffc000, v52
	v_cmp_gt_i32_e32 vcc, s2, v52
	v_lshl_add_u64 v[46:47], v[2:3], 0, v[54:55]
	global_load_dwordx4 v[30:33], v[46:47], off nt
	v_cndmask_b32_e32 v5, 0, v53, vcc
	v_cndmask_b32_e32 v4, v4, v52, vcc
	v_cndmask_b32_e32 v7, v76, v77, vcc
	v_cndmask_b32_e32 v6, v78, v79, vcc
	v_lshlrev_b64 v[2:3], 12, v[4:5]
	v_lshl_add_u64 v[2:3], v[6:7], 0, v[2:3]
	v_lshl_add_u64 v[2:3], v[2:3], 0, v[54:55]
	global_load_dwordx4 v[42:45], v[2:3], off nt
	global_load_dwordx4 v[22:25], v[2:3], off offset:1024 nt
	global_load_dwordx4 v[10:13], v[2:3], off offset:2048 nt
	s_nop 0
	global_load_dwordx4 v[2:5], v[2:3], off offset:3072 nt
	v_add_u32_e32 v68, s8, v52
	v_add_u32_e32 v6, 0xffffc000, v68
	v_ashrrev_i32_e32 v69, 31, v68
	v_cmp_gt_i32_e32 vcc, s2, v68
	v_lshlrev_b64 v[66:67], 11, v[66:67]
	v_lshl_add_u64 v[52:53], v[52:53], 0, s[12:13]
	v_cndmask_b32_e32 v7, 0, v69, vcc
	v_cndmask_b32_e32 v6, v6, v68, vcc
	v_cndmask_b32_e32 v9, v76, v77, vcc
	v_cndmask_b32_e32 v8, v78, v79, vcc
	v_lshlrev_b64 v[6:7], 12, v[6:7]
	v_lshl_add_u64 v[6:7], v[8:9], 0, v[6:7]
	v_lshl_add_u64 v[14:15], v[6:7], 0, v[54:55]
	global_load_dwordx4 v[38:41], v[14:15], off nt
	global_load_dwordx4 v[26:29], v[14:15], off offset:1024 nt
	global_load_dwordx4 v[6:9], v[14:15], off offset:3072 nt
	s_nop 0
	global_load_dwordx4 v[14:17], v[14:15], off offset:2048 nt
	s_nop 0
	global_load_dwordx4 v[18:21], v[46:47], off offset:1024 nt
	global_load_dwordx4 v[34:37], v[46:47], off offset:3072 nt
	s_nop 0
	global_load_dwordx4 v[46:49], v[46:47], off offset:2048 nt
	s_nop 0
	global_load_dwordx4 v[80:83], v[56:57], off
	global_load_dwordx4 v[120:123], v[56:57], off offset:1024
	global_load_dwordx4 v[124:127], v[56:57], off offset:2048
	global_load_dwordx4 v[128:131], v[56:57], off offset:3072
	v_lshlrev_b64 v[68:69], 11, v[68:69]
	s_waitcnt vmcnt(15)
	v_pk_mul_f32 v[84:85], v[32:33], v[32:33]
	v_pk_mul_f32 v[86:87], v[30:31], v[30:31]
	s_waitcnt vmcnt(14)
	v_pk_mul_f32 v[90:91], v[42:43], v[42:43]
	v_pk_mov_b32 v[88:89], v[86:87], v[84:85] op_sel:[1,0]
	v_mov_b32_e32 v87, v85
	v_pk_mul_f32 v[84:85], v[44:45], v[44:45]
	s_waitcnt vmcnt(13)
	v_pk_mul_f32 v[92:93], v[24:25], v[24:25]
	v_pk_mul_f32 v[94:95], v[22:23], v[22:23]
	v_pk_mov_b32 v[98:99], v[90:91], v[84:85] op_sel:[1,0]
	v_mov_b32_e32 v91, v85
	v_pk_mov_b32 v[84:85], v[94:95], v[92:93] op_sel:[1,0]
	v_mov_b32_e32 v95, v93
	s_waitcnt vmcnt(12)
	v_mul_f32_e32 v60, v11, v11
	v_mul_f32_e32 v96, v13, v13
	v_pk_add_f32 v[90:91], v[98:99], v[90:91]
	v_pk_add_f32 v[84:85], v[84:85], v[94:95]
	s_waitcnt vmcnt(11)
	v_mul_f32_e32 v109, v4, v4
	v_mul_f32_e32 v110, v5, v5
	v_mul_f32_e32 v111, v2, v2
	v_mul_f32_e32 v112, v3, v3
	v_pk_fma_f32 v[92:93], v[10:11], v[10:11], v[60:61] op_sel_hi:[1,1,0]
	v_pk_fma_f32 v[96:97], v[12:13], v[12:13], v[96:97] op_sel_hi:[1,1,0]
	s_waitcnt vmcnt(10)
	v_pk_mul_f32 v[100:101], v[40:41], v[40:41]
	v_pk_mul_f32 v[102:103], v[38:39], v[38:39]
	s_waitcnt vmcnt(9)
	v_pk_mul_f32 v[104:105], v[28:29], v[28:29]
	v_pk_mul_f32 v[106:107], v[26:27], v[26:27]
	v_pk_add_f32 v[90:91], v[90:91], v[90:91] op_sel:[0,1] op_sel_hi:[1,0]
	v_pk_add_f32 v[84:85], v[84:85], v[84:85] op_sel:[0,1] op_sel_hi:[1,0]
	v_mov_b32_e32 v93, v109
	v_mov_b32_e32 v97, v110
	v_pk_mov_b32 v[94:95], v[102:103], v[100:101] op_sel:[1,0]
	v_mov_b32_e32 v103, v101
	v_pk_mov_b32 v[98:99], v[106:107], v[104:105] op_sel:[1,0]
	v_mov_b32_e32 v107, v105
	v_mov_b32_e32 v91, v111
	v_mov_b32_e32 v85, v112
	v_pk_add_f32 v[92:93], v[92:93], v[96:97]
	v_pk_add_f32 v[94:95], v[94:95], v[102:103]
	v_pk_add_f32 v[96:97], v[98:99], v[106:107]
	v_pk_add_f32 v[84:85], v[90:91], v[84:85]
	s_waitcnt vmcnt(7)
	v_mul_f32_e32 v60, v15, v15
	v_mul_f32_e32 v108, v17, v17
	v_mul_f32_e32 v115, v6, v6
	v_mul_f32_e32 v116, v7, v7
	v_pk_add_f32 v[94:95], v[94:95], v[94:95] op_sel:[0,1] op_sel_hi:[1,0]
	v_pk_add_f32 v[96:97], v[96:97], v[96:97] op_sel:[0,1] op_sel_hi:[1,0]
	v_pk_add_f32 v[84:85], v[84:85], v[92:93]
	v_mul_f32_e32 v113, v8, v8
	v_mul_f32_e32 v114, v9, v9
	v_pk_fma_f32 v[100:101], v[14:15], v[14:15], v[60:61] op_sel_hi:[1,1,0]
	v_pk_fma_f32 v[104:105], v[16:17], v[16:17], v[108:109] op_sel_hi:[1,1,0]
	v_mov_b32_e32 v95, v115
	v_mov_b32_e32 v97, v116
	v_add_f32_e32 v60, v84, v85
	v_mov_b32_e32 v101, v113
	v_mov_b32_e32 v105, v114
	v_pk_add_f32 v[90:91], v[94:95], v[96:97]
	ds_bpermute_b32 v94, v70, v60
	v_pk_add_f32 v[98:99], v[100:101], v[104:105]
	v_pk_add_f32 v[86:87], v[88:89], v[86:87]
	v_pk_add_f32 v[84:85], v[90:91], v[98:99]
	s_waitcnt vmcnt(6)
	v_pk_mul_f32 v[88:89], v[20:21], v[20:21]
	v_pk_mul_f32 v[90:91], v[18:19], v[18:19]
	v_pk_add_f32 v[86:87], v[86:87], v[86:87] op_sel:[0,1] op_sel_hi:[1,0]
	v_pk_mov_b32 v[92:93], v[90:91], v[88:89] op_sel:[1,0]
	v_mov_b32_e32 v91, v89
	v_pk_add_f32 v[88:89], v[92:93], v[90:91]
	s_waitcnt vmcnt(5)
	v_mul_f32_e32 v90, v34, v34
	v_mul_f32_e32 v91, v35, v35
	v_mov_b32_e32 v87, v90
	v_pk_add_f32 v[88:89], v[88:89], v[88:89] op_sel:[0,1] op_sel_hi:[1,0]
	s_waitcnt lgkmcnt(0)
	v_add_f32_e32 v90, v60, v94
	v_mov_b32_e32 v89, v91
	ds_bpermute_b32 v91, v71, v90
	s_waitcnt vmcnt(4)
	v_mul_f32_e32 v60, v47, v47
	v_mul_f32_e32 v92, v36, v36
	v_pk_add_f32 v[86:87], v[86:87], v[88:89]
	v_pk_fma_f32 v[88:89], v[46:47], v[46:47], v[60:61] op_sel_hi:[1,1,0]
	v_mul_f32_e32 v60, v49, v49
	v_mul_f32_e32 v93, v37, v37
	v_mov_b32_e32 v89, v92
	s_waitcnt lgkmcnt(0)
	v_add_f32_e32 v92, v90, v91
	v_pk_fma_f32 v[90:91], v[48:49], v[48:49], v[60:61] op_sel_hi:[1,1,0]
	ds_bpermute_b32 v94, v72, v92
	v_mov_b32_e32 v91, v93
	v_pk_add_f32 v[88:89], v[88:89], v[90:91]
	s_waitcnt lgkmcnt(0)
	v_add_f32_e32 v60, v92, v94
	v_pk_add_f32 v[86:87], v[86:87], v[88:89]
	v_mov_b32_e32 v89, v84
	v_mov_b32_e32 v88, v86
	v_mov_b32_e32 v84, v87
	v_pk_add_f32 v[84:85], v[88:89], v[84:85]
	ds_bpermute_b32 v87, v70, v85
	ds_bpermute_b32 v86, v70, v84
	ds_bpermute_b32 v90, v73, v60
	s_waitcnt lgkmcnt(1)
	v_pk_add_f32 v[84:85], v[84:85], v[86:87]
	ds_bpermute_b32 v87, v71, v85
	ds_bpermute_b32 v86, v71, v84
	s_waitcnt lgkmcnt(2)
	v_add_f32_e32 v60, v60, v90
	ds_bpermute_b32 v88, v74, v60
	s_waitcnt lgkmcnt(1)
	v_pk_add_f32 v[84:85], v[84:85], v[86:87]
	ds_bpermute_b32 v87, v72, v85
	ds_bpermute_b32 v86, v72, v84
	s_waitcnt lgkmcnt(2)
	v_add_f32_e32 v60, v60, v88
	ds_bpermute_b32 v88, v75, v60
	s_waitcnt lgkmcnt(1)
	v_pk_add_f32 v[84:85], v[84:85], v[86:87]
	ds_bpermute_b32 v87, v73, v85
	ds_bpermute_b32 v86, v73, v84
	s_waitcnt lgkmcnt(2)
	v_add_f32_e32 v60, v60, v88
	v_fmamk_f32 v60, v60, 0x3a800000, v64
	v_mul_f32_e32 v88, 0x4b800000, v60
	v_cmp_gt_f32_e32 vcc, s3, v60
	s_waitcnt lgkmcnt(0)
	v_pk_add_f32 v[84:85], v[84:85], v[86:87]
	ds_bpermute_b32 v87, v74, v85
	ds_bpermute_b32 v86, v74, v84
	v_cndmask_b32_e32 v60, v60, v88, vcc
	v_rsq_f32_e32 v60, v60
	s_waitcnt lgkmcnt(0)
	v_pk_add_f32 v[84:85], v[84:85], v[86:87]
	ds_bpermute_b32 v87, v75, v85
	ds_bpermute_b32 v86, v75, v84
	v_mul_f32_e32 v88, 0x45800000, v60
	v_cndmask_b32_e32 v60, v60, v88, vcc
	v_pk_mul_f32 v[42:43], v[42:43], v[60:61] op_sel_hi:[1,0]
	v_pk_mul_f32 v[44:45], v[44:45], v[60:61] op_sel_hi:[1,0]
	s_waitcnt lgkmcnt(0)
	v_pk_add_f32 v[84:85], v[84:85], v[86:87]
	s_waitcnt vmcnt(0)
	v_pk_mul_f32 v[42:43], v[80:81], v[42:43]
	v_pk_fma_f32 v[84:85], v[84:85], s[18:19], v[64:65] op_sel_hi:[1,0,0]
	v_cvt_pk_bf16_f32 v42, v42, v43
	v_mul_f32_e32 v43, 0x4b800000, v85
	v_cmp_gt_f32_e32 vcc, s3, v85
	v_pk_mul_f32 v[44:45], v[82:83], v[44:45]
	v_pk_mul_f32 v[22:23], v[22:23], v[60:61] op_sel_hi:[1,0]
	v_cndmask_b32_e32 v43, v85, v43, vcc
	v_rsq_f32_e32 v85, v43
	v_cvt_pk_bf16_f32 v43, v44, v45
	global_store_dwordx2 v[62:63], v[42:43], off
	v_lshl_add_u64 v[42:43], v[58:59], 0, v[68:69]
	v_mul_f32_e32 v44, 0x45800000, v85
	v_cndmask_b32_e32 v44, v85, v44, vcc
	v_pk_mul_f32 v[38:39], v[38:39], v[44:45] op_sel_hi:[1,0]
	v_pk_mul_f32 v[40:41], v[40:41], v[44:45] op_sel_hi:[1,0]
	v_mul_f32_e32 v45, 0x4b800000, v84
	v_cmp_gt_f32_e32 vcc, s3, v84
	v_pk_mul_f32 v[40:41], v[82:83], v[40:41]
	v_pk_mul_f32 v[38:39], v[80:81], v[38:39]
	v_cndmask_b32_e32 v45, v84, v45, vcc
	v_rsq_f32_e32 v45, v45
	v_cvt_pk_bf16_f32 v38, v38, v39
	v_cvt_pk_bf16_f32 v39, v40, v41
	global_store_dwordx2 v[42:43], v[38:39], off
	v_mul_f32_e32 v38, 0x45800000, v45
	v_cndmask_b32_e32 v38, v45, v38, vcc
	v_pk_mul_f32 v[30:31], v[30:31], v[38:39] op_sel_hi:[1,0]
	v_pk_mul_f32 v[32:33], v[32:33], v[38:39] op_sel_hi:[1,0]
	v_pk_mul_f32 v[30:31], v[80:81], v[30:31]
	v_pk_mul_f32 v[32:33], v[82:83], v[32:33]
	v_cvt_pk_bf16_f32 v30, v30, v31
	v_cvt_pk_bf16_f32 v31, v32, v33
	v_lshl_add_u64 v[40:41], v[58:59], 0, v[66:67]
	global_store_dwordx2 v[40:41], v[30:31], off
	v_pk_mul_f32 v[24:25], v[24:25], v[60:61] op_sel_hi:[1,0]
	v_pk_mul_f32 v[26:27], v[26:27], v[44:45] op_sel_hi:[1,0]
	v_pk_mul_f32 v[28:29], v[28:29], v[44:45] op_sel_hi:[1,0]
	v_pk_mul_f32 v[18:19], v[18:19], v[38:39] op_sel_hi:[1,0]
	v_pk_mul_f32 v[20:21], v[20:21], v[38:39] op_sel_hi:[1,0]
	v_pk_mul_f32 v[10:11], v[10:11], v[60:61] op_sel_hi:[1,0]
	v_pk_mul_f32 v[12:13], v[12:13], v[60:61] op_sel_hi:[1,0]
	v_pk_mul_f32 v[14:15], v[14:15], v[44:45] op_sel_hi:[1,0]
	v_pk_mul_f32 v[16:17], v[16:17], v[44:45] op_sel_hi:[1,0]
	v_pk_mul_f32 v[2:3], v[2:3], v[60:61] op_sel_hi:[1,0]
	v_pk_mul_f32 v[4:5], v[4:5], v[60:61] op_sel_hi:[1,0]
	v_pk_mul_f32 v[6:7], v[6:7], v[44:45] op_sel_hi:[1,0]
	v_pk_mul_f32 v[8:9], v[8:9], v[44:45] op_sel_hi:[1,0]
	v_pk_mul_f32 v[24:25], v[122:123], v[24:25]
	v_pk_mul_f32 v[22:23], v[120:121], v[22:23]
	v_pk_mul_f32 v[28:29], v[122:123], v[28:29]
	v_pk_mul_f32 v[26:27], v[120:121], v[26:27]
	v_pk_mul_f32 v[20:21], v[122:123], v[20:21]
	v_pk_mul_f32 v[18:19], v[120:121], v[18:19]
	v_cvt_pk_bf16_f32 v22, v22, v23
	v_cvt_pk_bf16_f32 v23, v24, v25
	v_cvt_pk_bf16_f32 v24, v26, v27
	v_cvt_pk_bf16_f32 v25, v28, v29
	v_cvt_pk_bf16_f32 v18, v18, v19
	v_cvt_pk_bf16_f32 v19, v20, v21
	global_store_dwordx2 v[62:63], v[22:23], off offset:512
	global_store_dwordx2 v[42:43], v[24:25], off offset:512
	global_store_dwordx2 v[40:41], v[18:19], off offset:512
	v_pk_mul_f32 v[22:23], v[46:47], v[38:39] op_sel_hi:[1,0]
	v_pk_mul_f32 v[24:25], v[48:49], v[38:39] op_sel_hi:[1,0]
	v_pk_mul_f32 v[12:13], v[126:127], v[12:13]
	v_pk_mul_f32 v[10:11], v[124:125], v[10:11]
	v_pk_mul_f32 v[16:17], v[126:127], v[16:17]
	v_pk_mul_f32 v[14:15], v[124:125], v[14:15]
	v_pk_mul_f32 v[20:21], v[126:127], v[24:25]
	v_pk_mul_f32 v[18:19], v[124:125], v[22:23]
	v_cvt_pk_bf16_f32 v10, v10, v11
	v_cvt_pk_bf16_f32 v11, v12, v13
	v_cvt_pk_bf16_f32 v12, v14, v15
	v_cvt_pk_bf16_f32 v13, v16, v17
	v_cvt_pk_bf16_f32 v14, v18, v19
	v_cvt_pk_bf16_f32 v15, v20, v21
	global_store_dwordx2 v[62:63], v[10:11], off offset:1024
	global_store_dwordx2 v[42:43], v[12:13], off offset:1024
	global_store_dwordx2 v[40:41], v[14:15], off offset:1024
	v_add_u32_e32 v14, s0, v52
	v_cmp_lt_i32_e32 vcc, s4, v14
	v_pk_mul_f32 v[14:15], v[34:35], v[38:39] op_sel_hi:[1,0]
	v_pk_mul_f32 v[16:17], v[36:37], v[38:39] op_sel_hi:[1,0]
	s_or_b64 s[14:15], vcc, s[14:15]
	v_pk_mul_f32 v[4:5], v[4:5], v[130:131]
	v_pk_mul_f32 v[2:3], v[2:3], v[128:129]
	v_pk_mul_f32 v[8:9], v[8:9], v[130:131]
	v_pk_mul_f32 v[6:7], v[6:7], v[128:129]
	v_pk_mul_f32 v[12:13], v[16:17], v[130:131]
	v_pk_mul_f32 v[10:11], v[14:15], v[128:129]
	v_cvt_pk_bf16_f32 v2, v2, v3
	v_cvt_pk_bf16_f32 v3, v4, v5
	v_cvt_pk_bf16_f32 v4, v6, v7
	v_cvt_pk_bf16_f32 v5, v8, v9
	v_cvt_pk_bf16_f32 v6, v10, v11
	v_cvt_pk_bf16_f32 v7, v12, v13
	global_store_dwordx2 v[62:63], v[2:3], off offset:1536
	global_store_dwordx2 v[42:43], v[4:5], off offset:1536
	global_store_dwordx2 v[40:41], v[6:7], off offset:1536
	v_lshl_add_u64 v[62:63], v[62:63], 0, s[16:17]
	s_andn2_b64 exec, exec, s[14:15]
	s_cbranch_execz .LBB0_57
